# GEMM accumulator zeroing with 64-bit moves
# baseline (speedup 1.0000x reference)
; template <class Epi, class Sched, bool ALIGN_EPI = false, bool SP2 = false>
; __device__ __forceinline__ void gemm_phase(PG8_LAS unsigned char* lds, const Gemm g, const Sched& S, const Epi& E) {
;     ...
;         const bool has_next = S.next(ui + 1, nxt);
;         const char* nA = has_next ? (const char*)g.A + (size_t)nxt.pm * tstep : cA; const char* nB = has_next ? (const char*)g.Bt + (size_t)nxt.pn * tstep : cB;
;     ...
; #pragma unroll
;         for (int a = 0; a < 2; ++a)
; #pragma unroll
;             for (int b = 0; b < 2; ++b)
; #pragma unroll
;                 for (int m = 0; m < 4; ++m)
; #pragma unroll
;                     for (int n = 0; n < 2; ++n) acc[a][b][m][n] = (f32x4){0.f, 0.f, 0.f, 0.f};
.LBB0_165:
	s_ashr_i32 s17, s16, 31
	s_lshl_b64 s[18:19], s[16:17], 19
	s_add_u32 s18, s66, s18
	s_addc_u32 s19, s67, s19
	s_and_b64 s[20:21], s[2:3], exec
	s_cselect_b32 s17, s19, s25
	s_cselect_b32 s68, s18, s24
	s_ashr_i32 s15, s14, 31
	s_lshl_b64 s[20:21], s[14:15], 19
	s_add_u32 s20, s30, s20
	s_addc_u32 s21, s31, s21
	s_and_b64 s[28:29], s[2:3], exec
	s_cselect_b32 s15, s21, s27
	s_cselect_b32 s69, s20, s26
	s_add_u32 s24, s24, 0x40080
	s_addc_u32 s25, s25, 0
	s_add_u32 s76, s26, 0x100
	v_mov_b64_e32 v[2:3], 0
	v_mov_b64_e32 v[4:5], 0
	v_mov_b64_e32 v[6:7], 0
	v_mov_b64_e32 v[8:9], 0
	v_mov_b64_e32 v[10:11], 0
	v_mov_b64_e32 v[12:13], 0
	v_mov_b64_e32 v[14:15], 0
	v_mov_b64_e32 v[16:17], 0
	v_mov_b64_e32 v[18:19], 0
	v_mov_b64_e32 v[20:21], 0
	v_mov_b64_e32 v[22:23], 0
	v_mov_b64_e32 v[24:25], 0
	v_mov_b64_e32 v[26:27], 0
	v_mov_b64_e32 v[28:29], 0
	v_mov_b64_e32 v[30:31], 0
	v_mov_b64_e32 v[32:33], 0
	v_mov_b64_e32 v[34:35], 0
	v_mov_b64_e32 v[36:37], 0
	v_mov_b64_e32 v[38:39], 0
	v_mov_b64_e32 v[40:41], 0
	v_mov_b64_e32 v[42:43], 0
	v_mov_b64_e32 v[44:45], 0
	v_mov_b64_e32 v[46:47], 0
	v_mov_b64_e32 v[48:49], 0
	v_mov_b64_e32 v[50:51], 0
	v_mov_b64_e32 v[52:53], 0
	v_mov_b64_e32 v[54:55], 0
	v_mov_b64_e32 v[56:57], 0
	v_mov_b64_e32 v[58:59], 0
	v_mov_b64_e32 v[60:61], 0
	v_mov_b64_e32 v[62:63], 0
	v_mov_b64_e32 v[64:65], 0
	v_mov_b64_e32 v[66:67], 0
	v_mov_b64_e32 v[68:69], 0
	v_mov_b64_e32 v[70:71], 0
	v_mov_b64_e32 v[72:73], 0
	v_mov_b64_e32 v[74:75], 0
	v_mov_b64_e32 v[76:77], 0
	v_mov_b64_e32 v[78:79], 0
	v_mov_b64_e32 v[80:81], 0
	v_mov_b64_e32 v[82:83], 0
	v_mov_b64_e32 v[84:85], 0
	v_mov_b64_e32 v[86:87], 0
	v_mov_b64_e32 v[88:89], 0
	v_mov_b64_e32 v[90:91], 0
	v_mov_b64_e32 v[92:93], 0
	v_mov_b64_e32 v[94:95], 0
	v_mov_b64_e32 v[96:97], 0
	v_mov_b64_e32 v[98:99], 0
	v_mov_b64_e32 v[100:101], 0
	v_mov_b64_e32 v[102:103], 0
	v_mov_b64_e32 v[104:105], 0
	v_mov_b64_e32 v[106:107], 0
	v_mov_b64_e32 v[108:109], 0
	v_mov_b64_e32 v[110:111], 0
	v_mov_b64_e32 v[112:113], 0
	v_mov_b64_e32 v[114:115], 0
	v_mov_b64_e32 v[116:117], 0
	v_mov_b64_e32 v[118:119], 0
	v_mov_b64_e32 v[120:121], 0
	v_mov_b64_e32 v[122:123], 0
	v_mov_b64_e32 v[124:125], 0
	v_mov_b64_e32 v[126:127], 0
	v_mov_b64_e32 v[128:129], 0
	s_addc_u32 s77, s27, 0
	s_mov_b32 s78, -2

; template <class Epi, class Sched, bool ALIGN_EPI = false, bool SP2 = false>
; __device__ __forceinline__ void gemm_phase(PG8_LAS unsigned char* lds, const Gemm g, const Sched& S, const Epi& E) {
;     ...
; #pragma unroll
;         for (int a = 0; a < 2; ++a)
; #pragma unroll
;             for (int b = 0; b < 2; ++b)
; #pragma unroll
;                 for (int m = 0; m < 4; ++m)
; #pragma unroll
;                     for (int n = 0; n < 2; ++n) acc[a][b][m][n] = (f32x4){0.f, 0.f, 0.f, 0.f};
.LBB0_260:
	s_add_u32 s18, s18, 0xb0080
	s_addc_u32 s19, s19, 0
	s_add_u32 s68, s20, 0x100
	v_mov_b64_e32 v[2:3], 0
	v_mov_b64_e32 v[4:5], 0
	v_mov_b64_e32 v[6:7], 0
	v_mov_b64_e32 v[8:9], 0
	v_mov_b64_e32 v[10:11], 0
	v_mov_b64_e32 v[12:13], 0
	v_mov_b64_e32 v[14:15], 0
	v_mov_b64_e32 v[16:17], 0
	v_mov_b64_e32 v[18:19], 0
	v_mov_b64_e32 v[20:21], 0
	v_mov_b64_e32 v[22:23], 0
	v_mov_b64_e32 v[24:25], 0
	v_mov_b64_e32 v[26:27], 0
	v_mov_b64_e32 v[28:29], 0
	v_mov_b64_e32 v[30:31], 0
	v_mov_b64_e32 v[32:33], 0
	v_mov_b64_e32 v[34:35], 0
	v_mov_b64_e32 v[36:37], 0
	v_mov_b64_e32 v[38:39], 0
	v_mov_b64_e32 v[40:41], 0
	v_mov_b64_e32 v[42:43], 0
	v_mov_b64_e32 v[44:45], 0
	v_mov_b64_e32 v[46:47], 0
	v_mov_b64_e32 v[48:49], 0
	v_mov_b64_e32 v[50:51], 0
	v_mov_b64_e32 v[52:53], 0
	v_mov_b64_e32 v[54:55], 0
	v_mov_b64_e32 v[56:57], 0
	v_mov_b64_e32 v[58:59], 0
	v_mov_b64_e32 v[60:61], 0
	v_mov_b64_e32 v[62:63], 0
	v_mov_b64_e32 v[64:65], 0
	v_mov_b64_e32 v[66:67], 0
	v_mov_b64_e32 v[68:69], 0
	v_mov_b64_e32 v[70:71], 0
	v_mov_b64_e32 v[72:73], 0
	v_mov_b64_e32 v[74:75], 0
	v_mov_b64_e32 v[76:77], 0
	v_mov_b64_e32 v[78:79], 0
	v_mov_b64_e32 v[80:81], 0
	v_mov_b64_e32 v[82:83], 0
	v_mov_b64_e32 v[84:85], 0
	v_mov_b64_e32 v[86:87], 0
	v_mov_b64_e32 v[88:89], 0
	v_mov_b64_e32 v[90:91], 0
	v_mov_b64_e32 v[92:93], 0
	v_mov_b64_e32 v[94:95], 0
	v_mov_b64_e32 v[96:97], 0
	v_mov_b64_e32 v[98:99], 0
	v_mov_b64_e32 v[100:101], 0
	v_mov_b64_e32 v[102:103], 0
	v_mov_b64_e32 v[104:105], 0
	v_mov_b64_e32 v[106:107], 0
	v_mov_b64_e32 v[108:109], 0
	v_mov_b64_e32 v[110:111], 0
	v_mov_b64_e32 v[112:113], 0
	v_mov_b64_e32 v[114:115], 0
	v_mov_b64_e32 v[116:117], 0
	v_mov_b64_e32 v[118:119], 0
	v_mov_b64_e32 v[120:121], 0
	v_mov_b64_e32 v[122:123], 0
	v_mov_b64_e32 v[124:125], 0
	v_mov_b64_e32 v[126:127], 0
	v_mov_b64_e32 v[128:129], 0
	s_addc_u32 s69, s21, 0
	s_mov_b32 s76, -2

; template <class Epi, class Sched, bool ALIGN_EPI = false, bool SP2 = false>
; __device__ __forceinline__ void gemm_phase(PG8_LAS unsigned char* lds, const Gemm g, const Sched& S, const Epi& E) {
;     ...
; #pragma unroll
;         for (int a = 0; a < 2; ++a)
; #pragma unroll
;             for (int b = 0; b < 2; ++b)
; #pragma unroll
;                 for (int m = 0; m < 4; ++m)
; #pragma unroll
;                     for (int n = 0; n < 2; ++n) acc[a][b][m][n] = (f32x4){0.f, 0.f, 0.f, 0.f};
.LBB0_417:
	s_ashr_i32 s15, s14, 31
	s_lshl_b64 s[16:17], s[14:15], 19
	s_add_u32 s16, s94, s16
	s_addc_u32 s17, s95, s17
	s_and_b64 s[18:19], s[2:3], exec
	s_cselect_b32 s15, s17, s23
	s_cselect_b32 s55, s16, s22
	s_ashr_i32 s13, s12, 31
	s_lshl_b64 s[18:19], s[12:13], 19
	s_add_u32 s18, s28, s18
	s_addc_u32 s19, s29, s19
	s_and_b64 s[26:27], s[2:3], exec
	s_cselect_b32 s13, s19, s25
	s_cselect_b32 s68, s18, s24
	s_add_u32 s22, s22, 0x40080
	s_addc_u32 s23, s23, 0
	s_add_u32 s69, s24, 0x100
	v_mov_b64_e32 v[2:3], 0
	v_mov_b64_e32 v[4:5], 0
	v_mov_b64_e32 v[6:7], 0
	v_mov_b64_e32 v[8:9], 0
	v_mov_b64_e32 v[10:11], 0
	v_mov_b64_e32 v[12:13], 0
	v_mov_b64_e32 v[14:15], 0
	v_mov_b64_e32 v[16:17], 0
	v_mov_b64_e32 v[18:19], 0
	v_mov_b64_e32 v[20:21], 0
	v_mov_b64_e32 v[22:23], 0
	v_mov_b64_e32 v[24:25], 0
	v_mov_b64_e32 v[26:27], 0
	v_mov_b64_e32 v[28:29], 0
	v_mov_b64_e32 v[30:31], 0
	v_mov_b64_e32 v[32:33], 0
	v_mov_b64_e32 v[34:35], 0
	v_mov_b64_e32 v[36:37], 0
	v_mov_b64_e32 v[38:39], 0
	v_mov_b64_e32 v[40:41], 0
	v_mov_b64_e32 v[42:43], 0
	v_mov_b64_e32 v[44:45], 0
	v_mov_b64_e32 v[46:47], 0
	v_mov_b64_e32 v[48:49], 0
	v_mov_b64_e32 v[50:51], 0
	v_mov_b64_e32 v[52:53], 0
	v_mov_b64_e32 v[54:55], 0
	v_mov_b64_e32 v[56:57], 0
	v_mov_b64_e32 v[58:59], 0
	v_mov_b64_e32 v[60:61], 0
	v_mov_b64_e32 v[62:63], 0
	v_mov_b64_e32 v[64:65], 0
	v_mov_b64_e32 v[66:67], 0
	v_mov_b64_e32 v[68:69], 0
	v_mov_b64_e32 v[70:71], 0
	v_mov_b64_e32 v[72:73], 0
	v_mov_b64_e32 v[74:75], 0
	v_mov_b64_e32 v[76:77], 0
	v_mov_b64_e32 v[78:79], 0
	v_mov_b64_e32 v[80:81], 0
	v_mov_b64_e32 v[82:83], 0
	v_mov_b64_e32 v[84:85], 0
	v_mov_b64_e32 v[86:87], 0
	v_mov_b64_e32 v[88:89], 0
	v_mov_b64_e32 v[90:91], 0
	v_mov_b64_e32 v[92:93], 0
	v_mov_b64_e32 v[94:95], 0
	v_mov_b64_e32 v[96:97], 0
	v_mov_b64_e32 v[98:99], 0
	v_mov_b64_e32 v[100:101], 0
	v_mov_b64_e32 v[102:103], 0
	v_mov_b64_e32 v[104:105], 0
	v_mov_b64_e32 v[106:107], 0
	v_mov_b64_e32 v[108:109], 0
	v_mov_b64_e32 v[110:111], 0
	v_mov_b64_e32 v[112:113], 0
	v_mov_b64_e32 v[114:115], 0
	v_mov_b64_e32 v[116:117], 0
	v_mov_b64_e32 v[118:119], 0
	v_mov_b64_e32 v[120:121], 0
	v_mov_b64_e32 v[122:123], 0
	v_mov_b64_e32 v[124:125], 0
	v_mov_b64_e32 v[126:127], 0
	v_mov_b64_e32 v[128:129], 0
	s_addc_u32 s76, s25, 0
	s_mov_b32 s77, -2

; template <class Epi, class Sched, bool ALIGN_EPI = false, bool SP2 = false>
; __device__ __forceinline__ void gemm_phase(PG8_LAS unsigned char* lds, const Gemm g, const Sched& S, const Epi& E) {
;     ...
; #pragma unroll
;         for (int a = 0; a < 2; ++a)
; #pragma unroll
;             for (int b = 0; b < 2; ++b)
; #pragma unroll
;                 for (int m = 0; m < 4; ++m)
; #pragma unroll
;                     for (int n = 0; n < 2; ++n) acc[a][b][m][n] = (f32x4){0.f, 0.f, 0.f, 0.f};
.LBB0_441:
	s_ashr_i32 s19, s18, 31
	s_lshl_b64 s[20:21], s[18:19], 19
	s_add_u32 s20, s34, s20
	s_addc_u32 s21, s35, s21
	s_and_b64 s[22:23], s[2:3], exec
	s_cselect_b32 s19, s21, s29
	s_cselect_b32 s76, s20, s28
	s_ashr_i32 s17, s16, 31
	s_lshl_b64 s[22:23], s[16:17], 19
	s_add_u32 s22, s94, s22
	s_addc_u32 s23, s95, s23
	s_and_b64 s[30:31], s[2:3], exec
	s_cselect_b32 s17, s23, s27
	s_cselect_b32 s77, s22, s26
	s_add_u32 s78, s26, 0x100
	s_addc_u32 s79, s27, 0
	s_add_u32 s26, s28, 0x40080
	v_mov_b64_e32 v[2:3], 0
	v_mov_b64_e32 v[4:5], 0
	v_mov_b64_e32 v[6:7], 0
	v_mov_b64_e32 v[8:9], 0
	v_mov_b64_e32 v[10:11], 0
	v_mov_b64_e32 v[12:13], 0
	v_mov_b64_e32 v[14:15], 0
	v_mov_b64_e32 v[16:17], 0
	v_mov_b64_e32 v[18:19], 0
	v_mov_b64_e32 v[20:21], 0
	v_mov_b64_e32 v[22:23], 0
	v_mov_b64_e32 v[24:25], 0
	v_mov_b64_e32 v[26:27], 0
	v_mov_b64_e32 v[28:29], 0
	v_mov_b64_e32 v[30:31], 0
	v_mov_b64_e32 v[32:33], 0
	v_mov_b64_e32 v[34:35], 0
	v_mov_b64_e32 v[36:37], 0
	v_mov_b64_e32 v[38:39], 0
	v_mov_b64_e32 v[40:41], 0
	v_mov_b64_e32 v[42:43], 0
	v_mov_b64_e32 v[44:45], 0
	v_mov_b64_e32 v[46:47], 0
	v_mov_b64_e32 v[48:49], 0
	v_mov_b64_e32 v[50:51], 0
	v_mov_b64_e32 v[52:53], 0
	v_mov_b64_e32 v[54:55], 0
	v_mov_b64_e32 v[56:57], 0
	v_mov_b64_e32 v[58:59], 0
	v_mov_b64_e32 v[60:61], 0
	v_mov_b64_e32 v[62:63], 0
	v_mov_b64_e32 v[64:65], 0
	v_mov_b64_e32 v[66:67], 0
	v_mov_b64_e32 v[68:69], 0
	v_mov_b64_e32 v[70:71], 0
	v_mov_b64_e32 v[72:73], 0
	v_mov_b64_e32 v[74:75], 0
	v_mov_b64_e32 v[76:77], 0
	v_mov_b64_e32 v[78:79], 0
	v_mov_b64_e32 v[80:81], 0
	v_mov_b64_e32 v[82:83], 0
	v_mov_b64_e32 v[84:85], 0
	v_mov_b64_e32 v[86:87], 0
	v_mov_b64_e32 v[88:89], 0
	v_mov_b64_e32 v[90:91], 0
	v_mov_b64_e32 v[92:93], 0
	v_mov_b64_e32 v[94:95], 0
	v_mov_b64_e32 v[96:97], 0
	v_mov_b64_e32 v[98:99], 0
	v_mov_b64_e32 v[100:101], 0
	v_mov_b64_e32 v[102:103], 0
	v_mov_b64_e32 v[104:105], 0
	v_mov_b64_e32 v[106:107], 0
	v_mov_b64_e32 v[108:109], 0
	v_mov_b64_e32 v[110:111], 0
	v_mov_b64_e32 v[112:113], 0
	v_mov_b64_e32 v[114:115], 0
	v_mov_b64_e32 v[116:117], 0
	v_mov_b64_e32 v[118:119], 0
	v_mov_b64_e32 v[120:121], 0
	v_mov_b64_e32 v[122:123], 0
	v_mov_b64_e32 v[124:125], 0
	v_mov_b64_e32 v[126:127], 0
	v_mov_b64_e32 v[128:129], 0
	s_addc_u32 s27, s29, 0
	s_mov_b32 s81, -2

; template <class Epi, class Sched, bool ALIGN_EPI = false, bool SP2 = false>
; __device__ __forceinline__ void gemm_phase(PG8_LAS unsigned char* lds, const Gemm g, const Sched& S, const Epi& E) {
;     ...
; #pragma unroll
;         for (int a = 0; a < 2; ++a)
; #pragma unroll
;             for (int b = 0; b < 2; ++b)
; #pragma unroll
;                 for (int m = 0; m < 4; ++m)
; #pragma unroll
;                     for (int n = 0; n < 2; ++n) acc[a][b][m][n] = (f32x4){0.f, 0.f, 0.f, 0.f};
.LBB0_856:
	s_ashr_i32 s23, s22, 31
	s_lshl_b64 s[24:25], s[22:23], 19
	s_add_u32 s24, s38, s24
	s_addc_u32 s25, s39, s25
	s_and_b64 s[26:27], s[2:3], exec
	s_cselect_b32 s23, s25, s31
	s_cselect_b32 s58, s24, s30
	s_ashr_i32 s21, s20, 31
	s_lshl_b64 s[26:27], s[20:21], 19
	s_add_u32 s26, s40, s26
	s_addc_u32 s27, s41, s27
	s_and_b64 s[36:37], s[2:3], exec
	s_cselect_b32 s21, s27, s35
	s_cselect_b32 s59, s26, s34
	s_add_u32 s30, s30, 0x40080
	s_addc_u32 s31, s31, 0
	s_add_u32 s60, s34, 0x100
	v_mov_b64_e32 v[2:3], 0
	v_mov_b64_e32 v[4:5], 0
	v_mov_b64_e32 v[6:7], 0
	v_mov_b64_e32 v[8:9], 0
	v_mov_b64_e32 v[10:11], 0
	v_mov_b64_e32 v[12:13], 0
	v_mov_b64_e32 v[14:15], 0
	v_mov_b64_e32 v[16:17], 0
	v_mov_b64_e32 v[18:19], 0
	v_mov_b64_e32 v[20:21], 0
	v_mov_b64_e32 v[22:23], 0
	v_mov_b64_e32 v[24:25], 0
	v_mov_b64_e32 v[26:27], 0
	v_mov_b64_e32 v[28:29], 0
	v_mov_b64_e32 v[30:31], 0
	v_mov_b64_e32 v[32:33], 0
	v_mov_b64_e32 v[34:35], 0
	v_mov_b64_e32 v[36:37], 0
	v_mov_b64_e32 v[38:39], 0
	v_mov_b64_e32 v[40:41], 0
	v_mov_b64_e32 v[42:43], 0
	v_mov_b64_e32 v[44:45], 0
	v_mov_b64_e32 v[46:47], 0
	v_mov_b64_e32 v[48:49], 0
	v_mov_b64_e32 v[50:51], 0
	v_mov_b64_e32 v[52:53], 0
	v_mov_b64_e32 v[54:55], 0
	v_mov_b64_e32 v[56:57], 0
	v_mov_b64_e32 v[58:59], 0
	v_mov_b64_e32 v[60:61], 0
	v_mov_b64_e32 v[62:63], 0
	v_mov_b64_e32 v[64:65], 0
	v_mov_b64_e32 v[66:67], 0
	v_mov_b64_e32 v[68:69], 0
	v_mov_b64_e32 v[70:71], 0
	v_mov_b64_e32 v[72:73], 0
	v_mov_b64_e32 v[74:75], 0
	v_mov_b64_e32 v[76:77], 0
	v_mov_b64_e32 v[78:79], 0
	v_mov_b64_e32 v[80:81], 0
	v_mov_b64_e32 v[82:83], 0
	v_mov_b64_e32 v[84:85], 0
	v_mov_b64_e32 v[86:87], 0
	v_mov_b64_e32 v[88:89], 0
	v_mov_b64_e32 v[90:91], 0
	v_mov_b64_e32 v[92:93], 0
	v_mov_b64_e32 v[94:95], 0
	v_mov_b64_e32 v[96:97], 0
	v_mov_b64_e32 v[98:99], 0
	v_mov_b64_e32 v[100:101], 0
	v_mov_b64_e32 v[102:103], 0
	v_mov_b64_e32 v[104:105], 0
	v_mov_b64_e32 v[106:107], 0
	v_mov_b64_e32 v[108:109], 0
	v_mov_b64_e32 v[110:111], 0
	v_mov_b64_e32 v[112:113], 0
	v_mov_b64_e32 v[114:115], 0
	v_mov_b64_e32 v[116:117], 0
	v_mov_b64_e32 v[118:119], 0
	v_mov_b64_e32 v[120:121], 0
	v_mov_b64_e32 v[122:123], 0
	v_mov_b64_e32 v[124:125], 0
	v_mov_b64_e32 v[126:127], 0
	v_mov_b64_e32 v[128:129], 0
	s_addc_u32 s61, s35, 0
	s_mov_b32 s62, -2

; template <class Epi, class Sched, bool ALIGN_EPI = false, bool SP2 = false>
; __device__ __forceinline__ void gemm_phase(PG8_LAS unsigned char* lds, const Gemm g, const Sched& S, const Epi& E) {
;     ...
; #pragma unroll
;         for (int a = 0; a < 2; ++a)
; #pragma unroll
;             for (int b = 0; b < 2; ++b)
; #pragma unroll
;                 for (int m = 0; m < 4; ++m)
; #pragma unroll
;                     for (int n = 0; n < 2; ++n) acc[a][b][m][n] = (f32x4){0.f, 0.f, 0.f, 0.f};
.LBB0_1013:
	s_ashr_i32 s17, s16, 31
	s_lshl_b64 s[18:19], s[16:17], 19
	s_add_u32 s18, s66, s18
	s_addc_u32 s19, s67, s19
	s_and_b64 s[20:21], s[2:3], exec
	s_cselect_b32 s17, s19, s25
	s_cselect_b32 s48, s18, s24
	s_ashr_i32 s15, s14, 31
	s_lshl_b64 s[20:21], s[14:15], 19
	s_add_u32 s20, s30, s20
	s_addc_u32 s21, s31, s21
	s_and_b64 s[28:29], s[2:3], exec
	s_cselect_b32 s15, s21, s27
	s_cselect_b32 s49, s20, s26
	s_add_u32 s24, s24, 0x40080
	s_addc_u32 s25, s25, 0
	s_add_u32 s50, s26, 0x100
	v_mov_b64_e32 v[2:3], 0
	v_mov_b64_e32 v[4:5], 0
	v_mov_b64_e32 v[6:7], 0
	v_mov_b64_e32 v[8:9], 0
	v_mov_b64_e32 v[10:11], 0
	v_mov_b64_e32 v[12:13], 0
	v_mov_b64_e32 v[14:15], 0
	v_mov_b64_e32 v[16:17], 0
	v_mov_b64_e32 v[18:19], 0
	v_mov_b64_e32 v[20:21], 0
	v_mov_b64_e32 v[22:23], 0
	v_mov_b64_e32 v[24:25], 0
	v_mov_b64_e32 v[26:27], 0
	v_mov_b64_e32 v[28:29], 0
	v_mov_b64_e32 v[30:31], 0
	v_mov_b64_e32 v[32:33], 0
	v_mov_b64_e32 v[34:35], 0
	v_mov_b64_e32 v[36:37], 0
	v_mov_b64_e32 v[38:39], 0
	v_mov_b64_e32 v[40:41], 0
	v_mov_b64_e32 v[42:43], 0
	v_mov_b64_e32 v[44:45], 0
	v_mov_b64_e32 v[46:47], 0
	v_mov_b64_e32 v[48:49], 0
	v_mov_b64_e32 v[50:51], 0
	v_mov_b64_e32 v[52:53], 0
	v_mov_b64_e32 v[54:55], 0
	v_mov_b64_e32 v[56:57], 0
	v_mov_b64_e32 v[58:59], 0
	v_mov_b64_e32 v[60:61], 0
	v_mov_b64_e32 v[62:63], 0
	v_mov_b64_e32 v[64:65], 0
	v_mov_b64_e32 v[66:67], 0
	v_mov_b64_e32 v[68:69], 0
	v_mov_b64_e32 v[70:71], 0
	v_mov_b64_e32 v[72:73], 0
	v_mov_b64_e32 v[74:75], 0
	v_mov_b64_e32 v[76:77], 0
	v_mov_b64_e32 v[78:79], 0
	v_mov_b64_e32 v[80:81], 0
	v_mov_b64_e32 v[82:83], 0
	v_mov_b64_e32 v[84:85], 0
	v_mov_b64_e32 v[86:87], 0
	v_mov_b64_e32 v[88:89], 0
	v_mov_b64_e32 v[90:91], 0
	v_mov_b64_e32 v[92:93], 0
	v_mov_b64_e32 v[94:95], 0
	v_mov_b64_e32 v[96:97], 0
	v_mov_b64_e32 v[98:99], 0
	v_mov_b64_e32 v[100:101], 0
	v_mov_b64_e32 v[102:103], 0
	v_mov_b64_e32 v[104:105], 0
	v_mov_b64_e32 v[106:107], 0
	v_mov_b64_e32 v[108:109], 0
	v_mov_b64_e32 v[110:111], 0
	v_mov_b64_e32 v[112:113], 0
	v_mov_b64_e32 v[114:115], 0
	v_mov_b64_e32 v[116:117], 0
	v_mov_b64_e32 v[118:119], 0
	v_mov_b64_e32 v[120:121], 0
	v_mov_b64_e32 v[122:123], 0
	v_mov_b64_e32 v[124:125], 0
	v_mov_b64_e32 v[126:127], 0
	v_mov_b64_e32 v[128:129], 0
	s_addc_u32 s51, s27, 0
	s_mov_b32 s52, -2

; template <class Epi, class Sched, bool ALIGN_EPI = false, bool SP2 = false>
; __device__ __forceinline__ void gemm_phase(PG8_LAS unsigned char* lds, const Gemm g, const Sched& S, const Epi& E) {
;     ...
; #pragma unroll
;         for (int a = 0; a < 2; ++a)
; #pragma unroll
;             for (int b = 0; b < 2; ++b)
; #pragma unroll
;                 for (int m = 0; m < 4; ++m)
; #pragma unroll
;                     for (int n = 0; n < 2; ++n) acc[a][b][m][n] = (f32x4){0.f, 0.f, 0.f, 0.f};
.LBB0_1108:
	s_add_u32 s24, s24, 0xb0080
	s_addc_u32 s25, s25, 0
	s_add_u32 s56, s26, 0x100
	v_mov_b64_e32 v[2:3], 0
	v_mov_b64_e32 v[4:5], 0
	v_mov_b64_e32 v[6:7], 0
	v_mov_b64_e32 v[8:9], 0
	v_mov_b64_e32 v[10:11], 0
	v_mov_b64_e32 v[12:13], 0
	v_mov_b64_e32 v[14:15], 0
	v_mov_b64_e32 v[16:17], 0
	v_mov_b64_e32 v[18:19], 0
	v_mov_b64_e32 v[20:21], 0
	v_mov_b64_e32 v[22:23], 0
	v_mov_b64_e32 v[24:25], 0
	v_mov_b64_e32 v[26:27], 0
	v_mov_b64_e32 v[28:29], 0
	v_mov_b64_e32 v[30:31], 0
	v_mov_b64_e32 v[32:33], 0
	v_mov_b64_e32 v[34:35], 0
	v_mov_b64_e32 v[36:37], 0
	v_mov_b64_e32 v[38:39], 0
	v_mov_b64_e32 v[40:41], 0
	v_mov_b64_e32 v[42:43], 0
	v_mov_b64_e32 v[44:45], 0
	v_mov_b64_e32 v[46:47], 0
	v_mov_b64_e32 v[48:49], 0
	v_mov_b64_e32 v[50:51], 0
	v_mov_b64_e32 v[52:53], 0
	v_mov_b64_e32 v[54:55], 0
	v_mov_b64_e32 v[56:57], 0
	v_mov_b64_e32 v[58:59], 0
	v_mov_b64_e32 v[60:61], 0
	v_mov_b64_e32 v[62:63], 0
	v_mov_b64_e32 v[64:65], 0
	v_mov_b64_e32 v[66:67], 0
	v_mov_b64_e32 v[68:69], 0
	v_mov_b64_e32 v[70:71], 0
	v_mov_b64_e32 v[72:73], 0
	v_mov_b64_e32 v[74:75], 0
	v_mov_b64_e32 v[76:77], 0
	v_mov_b64_e32 v[78:79], 0
	v_mov_b64_e32 v[80:81], 0
	v_mov_b64_e32 v[82:83], 0
	v_mov_b64_e32 v[84:85], 0
	v_mov_b64_e32 v[86:87], 0
	v_mov_b64_e32 v[88:89], 0
	v_mov_b64_e32 v[90:91], 0
	v_mov_b64_e32 v[92:93], 0
	v_mov_b64_e32 v[94:95], 0
	v_mov_b64_e32 v[96:97], 0
	v_mov_b64_e32 v[98:99], 0
	v_mov_b64_e32 v[100:101], 0
	v_mov_b64_e32 v[102:103], 0
	v_mov_b64_e32 v[104:105], 0
	v_mov_b64_e32 v[106:107], 0
	v_mov_b64_e32 v[108:109], 0
	v_mov_b64_e32 v[110:111], 0
	v_mov_b64_e32 v[112:113], 0
	v_mov_b64_e32 v[114:115], 0
	v_mov_b64_e32 v[116:117], 0
	v_mov_b64_e32 v[118:119], 0
	v_mov_b64_e32 v[120:121], 0
	v_mov_b64_e32 v[122:123], 0
	v_mov_b64_e32 v[124:125], 0
	v_mov_b64_e32 v[126:127], 0
	v_mov_b64_e32 v[128:129], 0
	s_addc_u32 s57, s27, 0
	s_mov_b32 s58, -2
